# MLA PV block: the four per-fragment lgkmcnt waits of each MFMA group coalesced into one wait before the group (12 fewer s_waitcnt per tile)
# speedup vs baseline: 1.0057x; 1.0057x over previous
; #define PIN() do { asm volatile("" ::: "memory"); __builtin_amdgcn_sched_barrier(0); } while (0)
; #define MFMA(a, b, c) __builtin_amdgcn_mfma_f32_32x32x16_bf16((a), (b), (c), 0, 0, 0)
; DI unsigned pk2(float a, float b) { f32x2_t v = {a, b}; bf16x2_t r = __builtin_convertvector(v, bf16x2_t); return __builtin_bit_cast(unsigned, r); }
; #define VLD(dst_, s4_) do { _Pragma("unroll") for (int db = 0; db < 4; ++db) dst_[db].v = *(const bf16x8*)(vbase + db * 32 * VSTR + (s4_) * 32); } while (0)
; template <int DQK, int NM>
; DI void attn_item(const bf16_t* Qb, const bf16_t* Kb, size_t mstride, const bf16_t* VTb,
;                   int q0, int nkt, float cs, bf16_t* Orow  , float lam, float outscale, const float* subw, char* smem) {
;     ...
;     const char* vbase = cur + KT_BYTES + l31 * VSTR + hh * 16;
;     {
;       struct VF { bf16x8 v; };
;       VF vfa[4], vfb[4];
;     ...
;       VLD(vfa, 0);
; #pragma unroll
;       for (int s4 = 0; s4 < 4; ++s4) {
;         const int kb = s4 >> 1, sp = s4 & 1;
;         PIN();
;         if (s4 < 3) { if (s4 & 1) VLD(vfa, s4 + 1); else VLD(vfb, s4 + 1); }
;         union { bf16x8 v; unsigned u[4]; } pf;
; #pragma unroll
;         for (int e = 0; e < 4; ++e) pf.u[e] = pk2(sacc[kb][8 * sp + 2 * e], sacc[kb][8 * sp + 2 * e + 1]);
;         PIN();
; #pragma unroll
;         for (int db = 0; db < 4; ++db) { if (s4 & 1) oacc[db] = MFMA(vfb[db].v, pf.v, oacc[db]); else oacc[db] = MFMA(vfa[db].v, pf.v, oacc[db]); }
;         {
;           char* b_ = smem + ((kt + 1) & 1) * BUF;
;           if (s4 == 0) { *(uint4*)(b_ + klo[0]) = kreg0; if (NKC > 2) *(uint4*)(b_ + klo[2]) = kreg2; }
;           if (s4 == 1) { *(uint4*)(b_ + klo[1]) = kreg1; }
;           if (s4 == 2) { *(uint4*)(b_ + vlo0) = vreg0; }
;           if (s4 == 3) { *(uint4*)(b_ + vlo1) = vreg1; }
;         }
;       }
.LBB0_126:
	v_mul_f32_e32 v196, 0x3dd53b95, v218
	v_fma_f32 v80, v80, s26, -v196
	v_fma_f32 v81, v81, s26, -v196
	v_fma_f32 v64, v64, s26, -v196
	v_fma_f32 v65, v65, s26, -v196
	v_exp_f32_e32 v220, v80
	v_exp_f32_e32 v221, v81
	v_fma_f32 v80, v82, s26, -v196
	v_fma_f32 v81, v83, s26, -v196
	v_fma_f32 v82, v88, s26, -v196
	v_fma_f32 v83, v89, s26, -v196
	v_exp_f32_e32 v222, v80
	v_exp_f32_e32 v223, v81
	v_fma_f32 v80, v84, s26, -v196
	v_fma_f32 v81, v85, s26, -v196
	v_exp_f32_e32 v228, v82
	v_exp_f32_e32 v224, v80
	v_exp_f32_e32 v225, v81
	v_fma_f32 v80, v86, s26, -v196
	v_fma_f32 v81, v87, s26, -v196
	v_exp_f32_e32 v229, v83
	v_exp_f32_e32 v226, v80
	v_exp_f32_e32 v227, v81
	v_fma_f32 v82, v90, s26, -v196
	v_fma_f32 v83, v91, s26, -v196
	v_exp_f32_e32 v230, v82
	v_exp_f32_e32 v231, v83
	v_fma_f32 v82, v92, s26, -v196
	v_fma_f32 v83, v93, s26, -v196
	v_exp_f32_e32 v232, v82
	v_exp_f32_e32 v233, v83
	v_fma_f32 v82, v94, s26, -v196
	v_fma_f32 v83, v95, s26, -v196
	v_exp_f32_e32 v234, v82
	v_exp_f32_e32 v235, v83
	v_exp_f32_e32 v236, v64
	v_exp_f32_e32 v237, v65
	v_fma_f32 v64, v66, s26, -v196
	v_fma_f32 v65, v67, s26, -v196
	v_exp_f32_e32 v238, v64
	v_exp_f32_e32 v239, v65
	v_fma_f32 v64, v68, s26, -v196
	v_fma_f32 v65, v69, s26, -v196
	v_exp_f32_e32 v240, v64
	v_exp_f32_e32 v241, v65
	v_fma_f32 v64, v70, s26, -v196
	v_fma_f32 v65, v71, s26, -v196
	v_exp_f32_e32 v242, v64
	v_exp_f32_e32 v243, v65
	v_fma_f32 v66, v72, s26, -v196
	v_fma_f32 v67, v73, s26, -v196
	v_exp_f32_e32 v244, v66
	v_exp_f32_e32 v245, v67
	v_fma_f32 v66, v74, s26, -v196
	v_fma_f32 v67, v75, s26, -v196
	v_exp_f32_e32 v246, v66
	v_exp_f32_e32 v247, v67
	v_fma_f32 v66, v76, s26, -v196
	v_fma_f32 v67, v77, s26, -v196
	v_exp_f32_e32 v248, v66
	v_exp_f32_e32 v249, v67
	v_fma_f32 v66, v78, s26, -v196
	v_fma_f32 v67, v79, s26, -v196
	v_exp_f32_e32 v250, v66
	v_exp_f32_e32 v251, v67
	v_add3_u32 v219, s25, v214, v170
	ds_read_b128 v[64:67], v219 offset:25600
	ds_read_b128 v[68:71], v219 offset:30208
	ds_read_b128 v[72:75], v219 offset:34816
	ds_read_b128 v[76:79], v219 offset:39424
	s_add_i32 s24, s24, 0
	ds_read_b128 v[80:83], v219 offset:25632
	ds_read_b128 v[84:87], v219 offset:30240
	ds_read_b128 v[88:91], v219 offset:34848
	ds_read_b128 v[92:95], v219 offset:39456
	v_add_f32_e32 v203, v220, v221
	v_add_f32_e32 v203, v222, v203
	v_add_f32_e32 v203, v223, v203
	v_add_f32_e32 v203, v224, v203
	v_add_f32_e32 v203, v225, v203
	v_add_f32_e32 v203, v226, v203
	v_add_f32_e32 v203, v227, v203
	v_cvt_pk_bf16_f32 v220, v220, v221
	v_cvt_pk_bf16_f32 v221, v222, v223
	v_cvt_pk_bf16_f32 v222, v224, v225
	v_cvt_pk_bf16_f32 v223, v226, v227
	s_waitcnt lgkmcnt(4)
	s_nop 0
	v_mfma_f32_32x32x16_bf16 v[32:47], v[64:67], v[220:223], v[32:47]
	v_add_f32_e32 v203, v228, v203
	v_add_f32_e32 v203, v229, v203
	s_waitcnt vmcnt(4)
	ds_write_b128 v206, v[158:161]
	s_waitcnt vmcnt(2)
	ds_write_b128 v211, v[162:165]
	v_mfma_f32_32x32x16_bf16 v[48:63], v[68:71], v[220:223], v[48:63]
	v_add_f32_e32 v203, v230, v203
	v_add_f32_e32 v203, v231, v203
	v_mfma_f32_32x32x16_bf16 v[16:31], v[72:75], v[220:223], v[16:31]
	v_add_f32_e32 v203, v232, v203
	v_add_f32_e32 v203, v233, v203
	v_mfma_f32_32x32x16_bf16 v[0:15], v[76:79], v[220:223], v[0:15]
	v_add_f32_e32 v203, v234, v203
	v_add_f32_e32 v203, v235, v203
	ds_read_b128 v[64:67], v219 offset:25664
	ds_read_b128 v[68:71], v219 offset:30272
	ds_read_b128 v[72:75], v219 offset:34880
	ds_read_b128 v[76:79], v219 offset:39488
	v_cvt_pk_bf16_f32 v158, v228, v229
	v_cvt_pk_bf16_f32 v159, v230, v231
	v_cvt_pk_bf16_f32 v160, v232, v233
	v_cvt_pk_bf16_f32 v161, v234, v235
	s_waitcnt lgkmcnt(6)
	s_nop 0
	v_mfma_f32_32x32x16_bf16 v[32:47], v[80:83], v[158:161], v[32:47]
	v_add_f32_e32 v203, v236, v203
	v_add_f32_e32 v203, v237, v203
	v_add_u32_e32 v80, s24, v215
	ds_write_b128 v80, v[154:157]
	v_mfma_f32_32x32x16_bf16 v[48:63], v[84:87], v[158:161], v[48:63]
	v_add_f32_e32 v203, v238, v203
	v_add_f32_e32 v203, v239, v203
	v_mfma_f32_32x32x16_bf16 v[16:31], v[88:91], v[158:161], v[16:31]
	v_add_f32_e32 v203, v240, v203
	v_add_f32_e32 v203, v241, v203
	v_mfma_f32_32x32x16_bf16 v[0:15], v[92:95], v[158:161], v[0:15]
	v_add_f32_e32 v203, v242, v203
	v_add_f32_e32 v203, v243, v203
	ds_read_b128 v[80:83], v219 offset:25696
	ds_read_b128 v[84:87], v219 offset:30304
	ds_read_b128 v[88:91], v219 offset:34912
	ds_read_b128 v[92:95], v219 offset:39520
	v_cvt_pk_bf16_f32 v154, v236, v237
	v_cvt_pk_bf16_f32 v155, v238, v239
	v_cvt_pk_bf16_f32 v156, v240, v241
	v_cvt_pk_bf16_f32 v157, v242, v243
	s_waitcnt lgkmcnt(5)
	s_nop 0
	v_mfma_f32_32x32x16_bf16 v[32:47], v[64:67], v[154:157], v[32:47]
	v_add_f32_e32 v203, v244, v203
	v_add_f32_e32 v203, v245, v203
	v_add_u32_e32 v64, s24, v182
	s_waitcnt vmcnt(1)
	ds_write_b128 v64, v[150:153] offset:25600
	v_mfma_f32_32x32x16_bf16 v[48:63], v[68:71], v[154:157], v[48:63]
	v_add_f32_e32 v203, v246, v203
	v_add_f32_e32 v203, v247, v203
	v_mfma_f32_32x32x16_bf16 v[16:31], v[72:75], v[154:157], v[16:31]
	v_add_f32_e32 v203, v248, v203
	v_add_f32_e32 v203, v249, v203
	v_mfma_f32_32x32x16_bf16 v[0:15], v[76:79], v[154:157], v[0:15]
	v_add_f32_e32 v203, v250, v203
	v_add_f32_e32 v203, v251, v203
	v_cvt_pk_bf16_f32 v64, v244, v245
	v_cvt_pk_bf16_f32 v65, v246, v247
	v_cvt_pk_bf16_f32 v66, v248, v249
	v_cvt_pk_bf16_f32 v67, v250, v251
	s_waitcnt lgkmcnt(1)
	s_nop 0
	v_mfma_f32_32x32x16_bf16 v[32:47], v[80:83], v[64:67], v[32:47]
	v_add_u32_e32 v68, s24, v184
	s_waitcnt vmcnt(0)
	ds_write_b128 v68, v[146:149] offset:25600
	v_add_f32_e32 v185, v185, v203
	v_mfma_f32_32x32x16_bf16 v[48:63], v[84:87], v[64:67], v[48:63]
	v_mfma_f32_32x32x16_bf16 v[16:31], v[88:91], v[64:67], v[16:31]
	v_mfma_f32_32x32x16_bf16 v[0:15], v[92:95], v[64:67], v[0:15]
	s_cmpk_eq_i32 s37, 0x84
	s_waitcnt lgkmcnt(0)
	s_barrier
	s_cbranch_scc1 .LBB0_129
